# attention P.V: V fragment reads requested earlier (two before the exp chain, ring of seven buffers), row sums folded in place
# speedup vs baseline: 1.0317x; 1.0028x over previous
.LBB0_234:
	v_add_u32_e32 v238, s43, v179
	ds_read_b64_tr_b16 v[214:215], v238 offset:17408
	ds_read_b64_tr_b16 v[216:217], v238 offset:26112
	ds_read_b64_tr_b16 v[218:219], v238 offset:17440
	ds_read_b64_tr_b16 v[220:221], v238 offset:26144
	v_sub_f32_e32 v168, v198, v196
	v_exp_f32_e32 v223, v168
	v_sub_f32_e32 v168, v199, v196
	v_exp_f32_e32 v225, v168
	v_sub_f32_e32 v168, v200, v196
	v_exp_f32_e32 v227, v168
	v_sub_f32_e32 v168, v201, v196
	v_exp_f32_e32 v229, v168
	v_sub_f32_e32 v168, v202, v196
	v_exp_f32_e32 v231, v168
	v_sub_f32_e32 v168, v203, v196
	v_exp_f32_e32 v233, v168
	v_sub_f32_e32 v168, v204, v196
	v_exp_f32_e32 v235, v168
	v_sub_f32_e32 v168, v205, v196
	v_exp_f32_e32 v237, v168
	v_sub_f32_e32 v168, v206, v197
	v_exp_f32_e32 v222, v168
	v_sub_f32_e32 v168, v207, v197
	v_exp_f32_e32 v224, v168
	v_sub_f32_e32 v168, v208, v197
	v_exp_f32_e32 v226, v168
	v_sub_f32_e32 v168, v209, v197
	v_exp_f32_e32 v228, v168
	v_sub_f32_e32 v168, v210, v197
	v_exp_f32_e32 v230, v168
	v_sub_f32_e32 v168, v211, v197
	v_exp_f32_e32 v232, v168
	v_sub_f32_e32 v168, v212, v197
	v_exp_f32_e32 v234, v168
	v_sub_f32_e32 v168, v213, v197
	ds_read_b64_tr_b16 v[202:203], v238 offset:17472
	ds_read_b64_tr_b16 v[204:205], v238 offset:26176
	ds_read_b64_tr_b16 v[210:211], v238 offset:17504
	ds_read_b64_tr_b16 v[212:213], v238 offset:26208
	v_exp_f32_e32 v236, v168
	v_cvt_pk_bf16_f32 v198, v223, v225
	v_cvt_pk_bf16_f32 v199, v227, v229
	v_cvt_pk_bf16_f32 v200, v231, v233
	v_cvt_pk_bf16_f32 v201, v235, v237
	v_cvt_pk_bf16_f32 v206, v222, v224
	v_cvt_pk_bf16_f32 v207, v226, v228
	v_cvt_pk_bf16_f32 v208, v230, v232
	v_cvt_pk_bf16_f32 v209, v234, v236
	v_pk_add_f32 v[222:223], v[224:225], v[222:223]
	v_pk_add_f32 v[222:223], v[226:227], v[222:223]
	v_pk_add_f32 v[222:223], v[228:229], v[222:223]
	v_pk_add_f32 v[222:223], v[230:231], v[222:223]
	v_pk_add_f32 v[222:223], v[232:233], v[222:223]
	v_pk_add_f32 v[222:223], v[234:235], v[222:223]
	v_pk_add_f32 v[222:223], v[236:237], v[222:223]
	ds_read_b64_tr_b16 v[224:225], v238 offset:17536
	ds_read_b64_tr_b16 v[226:227], v238 offset:26240
	ds_read_b64_tr_b16 v[228:229], v238 offset:17568
	ds_read_b64_tr_b16 v[230:231], v238 offset:26272
	ds_read_b64_tr_b16 v[232:233], v238 offset:17600
	ds_read_b64_tr_b16 v[234:235], v238 offset:26304
	s_waitcnt lgkmcnt(12)
	v_mfma_f32_16x16x32_bf16 v[136:139], v[214:217], v[198:201], v[136:139]
	v_mfma_f32_16x16x32_bf16 v[128:131], v[214:217], v[206:209], v[128:131]
	ds_read_b64_tr_b16 v[214:215], v238 offset:17632
	ds_read_b64_tr_b16 v[216:217], v238 offset:26336
	s_waitcnt lgkmcnt(12)
	v_mfma_f32_16x16x32_bf16 v[120:123], v[218:221], v[198:201], v[120:123]
	v_mfma_f32_16x16x32_bf16 v[112:115], v[218:221], v[206:209], v[112:115]
	ds_read_b64_tr_b16 v[218:219], v238 offset:17664
	ds_read_b64_tr_b16 v[220:221], v238 offset:26368
	v_fma_f32 v164, v164, v166, v222
	v_fma_f32 v165, v165, v167, v223
	s_waitcnt lgkmcnt(12)
	v_mfma_f32_16x16x32_bf16 v[108:111], v[202:205], v[198:201], v[108:111]
	v_mfma_f32_16x16x32_bf16 v[104:107], v[202:205], v[206:209], v[104:107]
	ds_read_b64_tr_b16 v[202:203], v238 offset:17696
	ds_read_b64_tr_b16 v[204:205], v238 offset:26400
	s_waitcnt lgkmcnt(12)
	v_mfma_f32_16x16x32_bf16 v[100:103], v[210:213], v[198:201], v[100:103]
	v_mfma_f32_16x16x32_bf16 v[96:99], v[210:213], v[206:209], v[96:99]
	ds_read_b64_tr_b16 v[210:211], v238 offset:17728
	ds_read_b64_tr_b16 v[212:213], v238 offset:26432
	s_waitcnt lgkmcnt(12)
	v_mfma_f32_16x16x32_bf16 v[92:95], v[224:227], v[198:201], v[92:95]
	v_mfma_f32_16x16x32_bf16 v[88:91], v[224:227], v[206:209], v[88:91]
	ds_read_b64_tr_b16 v[224:225], v238 offset:17760
	ds_read_b64_tr_b16 v[226:227], v238 offset:26464
	s_waitcnt lgkmcnt(12)
	v_mfma_f32_16x16x32_bf16 v[84:87], v[228:231], v[198:201], v[84:87]
	v_mfma_f32_16x16x32_bf16 v[80:83], v[228:231], v[206:209], v[80:83]
	ds_read_b64_tr_b16 v[228:229], v238 offset:17792
	ds_read_b64_tr_b16 v[230:231], v238 offset:26496
	s_waitcnt lgkmcnt(12)
	v_mfma_f32_16x16x32_bf16 v[76:79], v[232:235], v[198:201], v[76:79]
	v_mfma_f32_16x16x32_bf16 v[72:75], v[232:235], v[206:209], v[72:75]
	ds_read_b64_tr_b16 v[232:233], v238 offset:17824
	ds_read_b64_tr_b16 v[234:235], v238 offset:26528
	s_waitcnt lgkmcnt(12)
	v_mfma_f32_16x16x32_bf16 v[68:71], v[214:217], v[198:201], v[68:71]
	v_mfma_f32_16x16x32_bf16 v[64:67], v[214:217], v[206:209], v[64:67]
	ds_read_b64_tr_b16 v[214:215], v238 offset:17856
	ds_read_b64_tr_b16 v[216:217], v238 offset:26560
	s_waitcnt lgkmcnt(12)
	v_mfma_f32_16x16x32_bf16 v[60:63], v[218:221], v[198:201], v[60:63]
	v_mfma_f32_16x16x32_bf16 v[56:59], v[218:221], v[206:209], v[56:59]
	ds_read_b64_tr_b16 v[218:219], v238 offset:17888
	ds_read_b64_tr_b16 v[220:221], v238 offset:26592
	s_waitcnt lgkmcnt(12)
	v_mfma_f32_16x16x32_bf16 v[48:51], v[202:205], v[198:201], v[48:51]
	v_mfma_f32_16x16x32_bf16 v[40:43], v[202:205], v[206:209], v[40:43]
	s_waitcnt lgkmcnt(10)
	v_mfma_f32_16x16x32_bf16 v[44:47], v[210:213], v[198:201], v[44:47]
	v_mfma_f32_16x16x32_bf16 v[52:55], v[210:213], v[206:209], v[52:55]
	s_waitcnt lgkmcnt(8)
	v_mfma_f32_16x16x32_bf16 v[28:31], v[224:227], v[198:201], v[28:31]
	v_mfma_f32_16x16x32_bf16 v[36:39], v[224:227], v[206:209], v[36:39]
	s_waitcnt lgkmcnt(6)
	v_mfma_f32_16x16x32_bf16 v[16:19], v[228:231], v[198:201], v[16:19]
	v_mfma_f32_16x16x32_bf16 v[32:35], v[228:231], v[206:209], v[32:35]
	s_waitcnt lgkmcnt(4)
	v_mfma_f32_16x16x32_bf16 v[8:11], v[232:235], v[198:201], v[8:11]
	v_mfma_f32_16x16x32_bf16 v[24:27], v[232:235], v[206:209], v[24:27]
	s_waitcnt lgkmcnt(2)
	v_mfma_f32_16x16x32_bf16 v[4:7], v[214:217], v[198:201], v[4:7]
	v_mfma_f32_16x16x32_bf16 v[20:23], v[214:217], v[206:209], v[20:23]
	s_waitcnt lgkmcnt(0)
	v_mfma_f32_16x16x32_bf16 v[0:3], v[218:221], v[198:201], v[0:3]
	v_mfma_f32_16x16x32_bf16 v[12:15], v[218:221], v[206:209], v[12:15]
	s_add_i32 s0, s40, -1
	s_cmp_ge_u32 s0, s38
	s_cbranch_scc0 .LBB0_236
	s_branch .LBB0_238
